# FFN-in SwiGLU epilogue hand-written: two register pairs interleaved (no hazard nops), store offsets as SGPR base + 32-bit VGPR offset
# speedup vs baseline: 1.0055x; 1.0002x over previous
.LBB0_641:
	v_lshl_add_u32 v148, s22, 8, v144
	v_lshl_or_b32 v151, s20, 7, v146
	v_mul_lo_u32 v148, v148, s71
	v_lshl_add_u32 v148, v151, 1, v148
	v_mul_f32_e32 v140, 0xbfb8aa3b, v120
	v_mul_f32_e32 v141, 0xbfb8aa3b, v121
	v_mul_f32_e32 v142, 0xbfb8aa3b, v122
	v_mul_f32_e32 v143, 0xbfb8aa3b, v123
	v_exp_f32_e32 v140, v140
	v_exp_f32_e32 v141, v141
	v_exp_f32_e32 v142, v142
	v_exp_f32_e32 v143, v143
	v_add_f32_e32 v140, 1.0, v140
	v_add_f32_e32 v141, 1.0, v141
	v_add_f32_e32 v142, 1.0, v142
	v_add_f32_e32 v143, 1.0, v143
	v_rcp_f32_e32 v140, v140
	v_rcp_f32_e32 v141, v141
	v_rcp_f32_e32 v142, v142
	v_rcp_f32_e32 v143, v143
	v_pk_mul_f32 v[120:121], v[120:121], v[140:141]
	v_pk_mul_f32 v[122:123], v[122:123], v[142:143]
	v_pk_mul_f32 v[120:121], v[120:121], v[124:125]
	v_pk_mul_f32 v[122:123], v[122:123], v[126:127]
	v_cvt_pk_bf16_f32 v120, v120, v121
	v_cvt_pk_bf16_f32 v121, v122, v123
	v_mul_f32_e32 v140, 0xbfb8aa3b, v112
	v_mul_f32_e32 v141, 0xbfb8aa3b, v113
	v_mul_f32_e32 v142, 0xbfb8aa3b, v114
	v_mul_f32_e32 v143, 0xbfb8aa3b, v115
	v_exp_f32_e32 v140, v140
	v_exp_f32_e32 v141, v141
	v_exp_f32_e32 v142, v142
	v_exp_f32_e32 v143, v143
	v_add_f32_e32 v140, 1.0, v140
	v_add_f32_e32 v141, 1.0, v141
	v_add_f32_e32 v142, 1.0, v142
	v_add_f32_e32 v143, 1.0, v143
	v_rcp_f32_e32 v140, v140
	v_rcp_f32_e32 v141, v141
	v_rcp_f32_e32 v142, v142
	v_rcp_f32_e32 v143, v143
	v_pk_mul_f32 v[112:113], v[112:113], v[140:141]
	v_pk_mul_f32 v[114:115], v[114:115], v[142:143]
	v_pk_mul_f32 v[112:113], v[112:113], v[116:117]
	v_pk_mul_f32 v[114:115], v[114:115], v[118:119]
	v_cvt_pk_bf16_f32 v122, v112, v113
	v_cvt_pk_bf16_f32 v123, v114, v115
	global_store_dwordx4 v148, v[120:123], s[8:9]
	v_mul_f32_e32 v140, 0xbfb8aa3b, v104
	v_mul_f32_e32 v141, 0xbfb8aa3b, v105
	v_mul_f32_e32 v142, 0xbfb8aa3b, v106
	v_mul_f32_e32 v143, 0xbfb8aa3b, v107
	v_exp_f32_e32 v140, v140
	v_exp_f32_e32 v141, v141
	v_exp_f32_e32 v142, v142
	v_exp_f32_e32 v143, v143
	v_add_f32_e32 v140, 1.0, v140
	v_add_f32_e32 v141, 1.0, v141
	v_add_f32_e32 v142, 1.0, v142
	v_add_f32_e32 v143, 1.0, v143
	v_rcp_f32_e32 v140, v140
	v_rcp_f32_e32 v141, v141
	v_rcp_f32_e32 v142, v142
	v_rcp_f32_e32 v143, v143
	v_pk_mul_f32 v[104:105], v[104:105], v[140:141]
	v_pk_mul_f32 v[106:107], v[106:107], v[142:143]
	v_pk_mul_f32 v[104:105], v[104:105], v[108:109]
	v_pk_mul_f32 v[106:107], v[106:107], v[110:111]
	v_cvt_pk_bf16_f32 v104, v104, v105
	v_cvt_pk_bf16_f32 v105, v106, v107
	v_mul_f32_e32 v140, 0xbfb8aa3b, v96
	v_mul_f32_e32 v141, 0xbfb8aa3b, v97
	v_mul_f32_e32 v142, 0xbfb8aa3b, v98
	v_mul_f32_e32 v143, 0xbfb8aa3b, v99
	v_exp_f32_e32 v140, v140
	v_exp_f32_e32 v141, v141
	v_exp_f32_e32 v142, v142
	v_exp_f32_e32 v143, v143
	v_add_f32_e32 v140, 1.0, v140
	v_add_f32_e32 v141, 1.0, v141
	v_add_f32_e32 v142, 1.0, v142
	v_add_f32_e32 v143, 1.0, v143
	v_rcp_f32_e32 v140, v140
	v_rcp_f32_e32 v141, v141
	v_rcp_f32_e32 v142, v142
	v_rcp_f32_e32 v143, v143
	v_pk_mul_f32 v[96:97], v[96:97], v[140:141]
	v_pk_mul_f32 v[98:99], v[98:99], v[142:143]
	v_pk_mul_f32 v[96:97], v[96:97], v[100:101]
	v_pk_mul_f32 v[98:99], v[98:99], v[102:103]
	v_cvt_pk_bf16_f32 v106, v96, v97
	v_cvt_pk_bf16_f32 v107, v98, v99
	v_add_u32_e32 v151, 0x16000, v148
	global_store_dwordx4 v151, v[104:107], s[8:9]
	v_mul_f32_e32 v140, 0xbfb8aa3b, v88
	v_mul_f32_e32 v141, 0xbfb8aa3b, v89
	v_mul_f32_e32 v142, 0xbfb8aa3b, v90
	v_mul_f32_e32 v143, 0xbfb8aa3b, v91
	v_exp_f32_e32 v140, v140
	v_exp_f32_e32 v141, v141
	v_exp_f32_e32 v142, v142
	v_exp_f32_e32 v143, v143
	v_add_f32_e32 v140, 1.0, v140
	v_add_f32_e32 v141, 1.0, v141
	v_add_f32_e32 v142, 1.0, v142
	v_add_f32_e32 v143, 1.0, v143
	v_rcp_f32_e32 v140, v140
	v_rcp_f32_e32 v141, v141
	v_rcp_f32_e32 v142, v142
	v_rcp_f32_e32 v143, v143
	v_pk_mul_f32 v[88:89], v[88:89], v[140:141]
	v_pk_mul_f32 v[90:91], v[90:91], v[142:143]
	v_pk_mul_f32 v[88:89], v[88:89], v[92:93]
	v_pk_mul_f32 v[90:91], v[90:91], v[94:95]
	v_cvt_pk_bf16_f32 v88, v88, v89
	v_cvt_pk_bf16_f32 v89, v90, v91
	v_mul_f32_e32 v140, 0xbfb8aa3b, v80
	v_mul_f32_e32 v141, 0xbfb8aa3b, v81
	v_mul_f32_e32 v142, 0xbfb8aa3b, v82
	v_mul_f32_e32 v143, 0xbfb8aa3b, v83
	v_exp_f32_e32 v140, v140
	v_exp_f32_e32 v141, v141
	v_exp_f32_e32 v142, v142
	v_exp_f32_e32 v143, v143
	v_add_f32_e32 v140, 1.0, v140
	v_add_f32_e32 v141, 1.0, v141
	v_add_f32_e32 v142, 1.0, v142
	v_add_f32_e32 v143, 1.0, v143
	v_rcp_f32_e32 v140, v140
	v_rcp_f32_e32 v141, v141
	v_rcp_f32_e32 v142, v142
	v_rcp_f32_e32 v143, v143
	v_pk_mul_f32 v[80:81], v[80:81], v[140:141]
	v_pk_mul_f32 v[82:83], v[82:83], v[142:143]
	v_pk_mul_f32 v[80:81], v[80:81], v[84:85]
	v_pk_mul_f32 v[82:83], v[82:83], v[86:87]
	v_cvt_pk_bf16_f32 v90, v80, v81
	v_cvt_pk_bf16_f32 v91, v82, v83
	v_add_u32_e32 v150, 0x2c000, v148
	global_store_dwordx4 v150, v[88:91], s[8:9]
	v_mul_f32_e32 v140, 0xbfb8aa3b, v72
	v_mul_f32_e32 v141, 0xbfb8aa3b, v73
	v_mul_f32_e32 v142, 0xbfb8aa3b, v74
	v_mul_f32_e32 v143, 0xbfb8aa3b, v75
	v_exp_f32_e32 v140, v140
	v_exp_f32_e32 v141, v141
	v_exp_f32_e32 v142, v142
	v_exp_f32_e32 v143, v143
	v_add_f32_e32 v140, 1.0, v140
	v_add_f32_e32 v141, 1.0, v141
	v_add_f32_e32 v142, 1.0, v142
	v_add_f32_e32 v143, 1.0, v143
	v_rcp_f32_e32 v140, v140
	v_rcp_f32_e32 v141, v141
	v_rcp_f32_e32 v142, v142
	v_rcp_f32_e32 v143, v143
	v_pk_mul_f32 v[72:73], v[72:73], v[140:141]
	v_pk_mul_f32 v[74:75], v[74:75], v[142:143]
	v_pk_mul_f32 v[72:73], v[72:73], v[76:77]
	v_pk_mul_f32 v[74:75], v[74:75], v[78:79]
	v_cvt_pk_bf16_f32 v72, v72, v73
	v_cvt_pk_bf16_f32 v73, v74, v75
	v_mul_f32_e32 v140, 0xbfb8aa3b, v64
	v_mul_f32_e32 v141, 0xbfb8aa3b, v65
	v_mul_f32_e32 v142, 0xbfb8aa3b, v66
	v_mul_f32_e32 v143, 0xbfb8aa3b, v67
	v_exp_f32_e32 v140, v140
	v_exp_f32_e32 v141, v141
	v_exp_f32_e32 v142, v142
	v_exp_f32_e32 v143, v143
	v_add_f32_e32 v140, 1.0, v140
	v_add_f32_e32 v141, 1.0, v141
	v_add_f32_e32 v142, 1.0, v142
	v_add_f32_e32 v143, 1.0, v143
	v_rcp_f32_e32 v140, v140
	v_rcp_f32_e32 v141, v141
	v_rcp_f32_e32 v142, v142
	v_rcp_f32_e32 v143, v143
	v_pk_mul_f32 v[64:65], v[64:65], v[140:141]
	v_pk_mul_f32 v[66:67], v[66:67], v[142:143]
	v_pk_mul_f32 v[64:65], v[64:65], v[68:69]
	v_pk_mul_f32 v[66:67], v[66:67], v[70:71]
	v_cvt_pk_bf16_f32 v74, v64, v65
	v_cvt_pk_bf16_f32 v75, v66, v67
	v_add_u32_e32 v151, 0x42000, v148
	global_store_dwordx4 v151, v[72:75], s[8:9]
	v_mul_f32_e32 v140, 0xbfb8aa3b, v56
	v_mul_f32_e32 v141, 0xbfb8aa3b, v57
	v_mul_f32_e32 v142, 0xbfb8aa3b, v58
	v_mul_f32_e32 v143, 0xbfb8aa3b, v59
	v_exp_f32_e32 v140, v140
	v_exp_f32_e32 v141, v141
	v_exp_f32_e32 v142, v142
	v_exp_f32_e32 v143, v143
	v_add_f32_e32 v140, 1.0, v140
	v_add_f32_e32 v141, 1.0, v141
	v_add_f32_e32 v142, 1.0, v142
	v_add_f32_e32 v143, 1.0, v143
	v_rcp_f32_e32 v140, v140
	v_rcp_f32_e32 v141, v141
	v_rcp_f32_e32 v142, v142
	v_rcp_f32_e32 v143, v143
	v_pk_mul_f32 v[56:57], v[56:57], v[140:141]
	v_pk_mul_f32 v[58:59], v[58:59], v[142:143]
	v_pk_mul_f32 v[56:57], v[56:57], v[60:61]
	v_pk_mul_f32 v[58:59], v[58:59], v[62:63]
	v_cvt_pk_bf16_f32 v56, v56, v57
	v_cvt_pk_bf16_f32 v57, v58, v59
	v_mul_f32_e32 v140, 0xbfb8aa3b, v48
	v_mul_f32_e32 v141, 0xbfb8aa3b, v49
	v_mul_f32_e32 v142, 0xbfb8aa3b, v50
	v_mul_f32_e32 v143, 0xbfb8aa3b, v51
	v_exp_f32_e32 v140, v140
	v_exp_f32_e32 v141, v141
	v_exp_f32_e32 v142, v142
	v_exp_f32_e32 v143, v143
	v_add_f32_e32 v140, 1.0, v140
	v_add_f32_e32 v141, 1.0, v141
	v_add_f32_e32 v142, 1.0, v142
	v_add_f32_e32 v143, 1.0, v143
	v_rcp_f32_e32 v140, v140
	v_rcp_f32_e32 v141, v141
	v_rcp_f32_e32 v142, v142
	v_rcp_f32_e32 v143, v143
	v_pk_mul_f32 v[48:49], v[48:49], v[140:141]
	v_pk_mul_f32 v[50:51], v[50:51], v[142:143]
	v_pk_mul_f32 v[48:49], v[48:49], v[52:53]
	v_pk_mul_f32 v[50:51], v[50:51], v[54:55]
	v_cvt_pk_bf16_f32 v58, v48, v49
	v_cvt_pk_bf16_f32 v59, v50, v51
	v_add_u32_e32 v150, 0xb0000, v148
	global_store_dwordx4 v150, v[56:59], s[8:9]
	v_mul_f32_e32 v140, 0xbfb8aa3b, v40
	v_mul_f32_e32 v141, 0xbfb8aa3b, v41
	v_mul_f32_e32 v142, 0xbfb8aa3b, v42
	v_mul_f32_e32 v143, 0xbfb8aa3b, v43
	v_exp_f32_e32 v140, v140
	v_exp_f32_e32 v141, v141
	v_exp_f32_e32 v142, v142
	v_exp_f32_e32 v143, v143
	v_add_f32_e32 v140, 1.0, v140
	v_add_f32_e32 v141, 1.0, v141
	v_add_f32_e32 v142, 1.0, v142
	v_add_f32_e32 v143, 1.0, v143
	v_rcp_f32_e32 v140, v140
	v_rcp_f32_e32 v141, v141
	v_rcp_f32_e32 v142, v142
	v_rcp_f32_e32 v143, v143
	v_pk_mul_f32 v[40:41], v[40:41], v[140:141]
	v_pk_mul_f32 v[42:43], v[42:43], v[142:143]
	v_pk_mul_f32 v[40:41], v[40:41], v[44:45]
	v_pk_mul_f32 v[42:43], v[42:43], v[46:47]
	v_cvt_pk_bf16_f32 v40, v40, v41
	v_cvt_pk_bf16_f32 v41, v42, v43
	v_mul_f32_e32 v140, 0xbfb8aa3b, v32
	v_mul_f32_e32 v141, 0xbfb8aa3b, v33
	v_mul_f32_e32 v142, 0xbfb8aa3b, v34
	v_mul_f32_e32 v143, 0xbfb8aa3b, v35
	v_exp_f32_e32 v140, v140
	v_exp_f32_e32 v141, v141
	v_exp_f32_e32 v142, v142
	v_exp_f32_e32 v143, v143
	v_add_f32_e32 v140, 1.0, v140
	v_add_f32_e32 v141, 1.0, v141
	v_add_f32_e32 v142, 1.0, v142
	v_add_f32_e32 v143, 1.0, v143
	v_rcp_f32_e32 v140, v140
	v_rcp_f32_e32 v141, v141
	v_rcp_f32_e32 v142, v142
	v_rcp_f32_e32 v143, v143
	v_pk_mul_f32 v[32:33], v[32:33], v[140:141]
	v_pk_mul_f32 v[34:35], v[34:35], v[142:143]
	v_pk_mul_f32 v[32:33], v[32:33], v[36:37]
	v_pk_mul_f32 v[34:35], v[34:35], v[38:39]
	v_cvt_pk_bf16_f32 v42, v32, v33
	v_cvt_pk_bf16_f32 v43, v34, v35
	v_add_u32_e32 v151, 0xc6000, v148
	global_store_dwordx4 v151, v[40:43], s[8:9]
	v_mul_f32_e32 v140, 0xbfb8aa3b, v24
	v_mul_f32_e32 v141, 0xbfb8aa3b, v25
	v_mul_f32_e32 v142, 0xbfb8aa3b, v26
	v_mul_f32_e32 v143, 0xbfb8aa3b, v27
	v_exp_f32_e32 v140, v140
	v_exp_f32_e32 v141, v141
	v_exp_f32_e32 v142, v142
	v_exp_f32_e32 v143, v143
	v_add_f32_e32 v140, 1.0, v140
	v_add_f32_e32 v141, 1.0, v141
	v_add_f32_e32 v142, 1.0, v142
	v_add_f32_e32 v143, 1.0, v143
	v_rcp_f32_e32 v140, v140
	v_rcp_f32_e32 v141, v141
	v_rcp_f32_e32 v142, v142
	v_rcp_f32_e32 v143, v143
	v_pk_mul_f32 v[24:25], v[24:25], v[140:141]
	v_pk_mul_f32 v[26:27], v[26:27], v[142:143]
	v_pk_mul_f32 v[24:25], v[24:25], v[28:29]
	v_pk_mul_f32 v[26:27], v[26:27], v[30:31]
	v_cvt_pk_bf16_f32 v24, v24, v25
	v_cvt_pk_bf16_f32 v25, v26, v27
	v_mul_f32_e32 v140, 0xbfb8aa3b, v16
	v_mul_f32_e32 v141, 0xbfb8aa3b, v17
	v_mul_f32_e32 v142, 0xbfb8aa3b, v18
	v_mul_f32_e32 v143, 0xbfb8aa3b, v19
	v_exp_f32_e32 v140, v140
	v_exp_f32_e32 v141, v141
	v_exp_f32_e32 v142, v142
	v_exp_f32_e32 v143, v143
	v_add_f32_e32 v140, 1.0, v140
	v_add_f32_e32 v141, 1.0, v141
	v_add_f32_e32 v142, 1.0, v142
	v_add_f32_e32 v143, 1.0, v143
	v_rcp_f32_e32 v140, v140
	v_rcp_f32_e32 v141, v141
	v_rcp_f32_e32 v142, v142
	v_rcp_f32_e32 v143, v143
	v_pk_mul_f32 v[16:17], v[16:17], v[140:141]
	v_pk_mul_f32 v[18:19], v[18:19], v[142:143]
	v_pk_mul_f32 v[16:17], v[16:17], v[20:21]
	v_pk_mul_f32 v[18:19], v[18:19], v[22:23]
	v_cvt_pk_bf16_f32 v26, v16, v17
	v_cvt_pk_bf16_f32 v27, v18, v19
	v_add_u32_e32 v150, 0xdc000, v148
	global_store_dwordx4 v150, v[24:27], s[8:9]
	v_mul_f32_e32 v140, 0xbfb8aa3b, v8
	v_mul_f32_e32 v141, 0xbfb8aa3b, v9
	v_mul_f32_e32 v142, 0xbfb8aa3b, v10
	v_mul_f32_e32 v143, 0xbfb8aa3b, v11
	v_exp_f32_e32 v140, v140
	v_exp_f32_e32 v141, v141
	v_exp_f32_e32 v142, v142
	v_exp_f32_e32 v143, v143
	v_add_f32_e32 v140, 1.0, v140
	v_add_f32_e32 v141, 1.0, v141
	v_add_f32_e32 v142, 1.0, v142
	v_add_f32_e32 v143, 1.0, v143
	v_rcp_f32_e32 v140, v140
	v_rcp_f32_e32 v141, v141
	v_rcp_f32_e32 v142, v142
	v_rcp_f32_e32 v143, v143
	v_pk_mul_f32 v[8:9], v[8:9], v[140:141]
	v_pk_mul_f32 v[10:11], v[10:11], v[142:143]
	v_pk_mul_f32 v[8:9], v[8:9], v[12:13]
	v_pk_mul_f32 v[10:11], v[10:11], v[14:15]
	v_cvt_pk_bf16_f32 v8, v8, v9
	v_cvt_pk_bf16_f32 v9, v10, v11
	v_mul_f32_e32 v140, 0xbfb8aa3b, v0
	v_mul_f32_e32 v141, 0xbfb8aa3b, v1
	v_mul_f32_e32 v142, 0xbfb8aa3b, v2
	v_mul_f32_e32 v143, 0xbfb8aa3b, v3
	v_exp_f32_e32 v140, v140
	v_exp_f32_e32 v141, v141
	v_exp_f32_e32 v142, v142
	v_exp_f32_e32 v143, v143
	v_add_f32_e32 v140, 1.0, v140
	v_add_f32_e32 v141, 1.0, v141
	v_add_f32_e32 v142, 1.0, v142
	v_add_f32_e32 v143, 1.0, v143
	v_rcp_f32_e32 v140, v140
	v_rcp_f32_e32 v141, v141
	v_rcp_f32_e32 v142, v142
	v_rcp_f32_e32 v143, v143
	v_pk_mul_f32 v[0:1], v[0:1], v[140:141]
	v_pk_mul_f32 v[2:3], v[2:3], v[142:143]
	v_pk_mul_f32 v[0:1], v[0:1], v[4:5]
	v_pk_mul_f32 v[2:3], v[2:3], v[6:7]
	v_cvt_pk_bf16_f32 v10, v0, v1
	v_cvt_pk_bf16_f32 v11, v2, v3
	v_add_u32_e32 v151, 0xf2000, v148
	global_store_dwordx4 v151, v[8:11], s[8:9]
	s_mov_b64 s[22:23], -1
	s_andn2_b64 vcc, exec, s[6:7]
	s_cbranch_vccnz .LBB0_634
	s_andn2_b64 vcc, exec, s[2:3]
	v_mov_b32 v120, 0
	v_mov_b32 v112, 0
	v_mov_b32 v104, 0
	v_mov_b32 v96, 0
	v_mov_b32 v88, 0
	v_mov_b32 v80, 0
	v_mov_b32 v72, 0
	v_mov_b32 v64, 0
	v_mov_b32 v124, 0
	v_mov_b32 v116, 0
	v_mov_b32 v108, 0
	v_mov_b32 v100, 0
	v_mov_b32 v92, 0
	v_mov_b32 v84, 0
	v_mov_b32 v76, 0
	v_mov_b32 v68, 0
	v_mov_b32 v56, 0
	v_mov_b32 v48, 0
	v_mov_b32 v40, 0
	v_mov_b32 v32, 0
	v_mov_b32 v24, 0
	v_mov_b32 v16, 0
	v_mov_b32 v8, 0
	v_mov_b32 v0, 0
	v_mov_b32 v60, 0
	v_mov_b32 v52, 0
	v_mov_b32 v44, 0
	v_mov_b32 v36, 0
	v_mov_b32 v28, 0
	v_mov_b32 v20, 0
	v_mov_b32 v12, 0
	v_mov_b32 v4, 0
	s_cbranch_vccnz .LBB0_633
	s_barrier
	s_branch .LBB0_633
